# dense attention loops: K/V global pointer advances moved from the loop head to the pre-barrier bookkeeping at the bottom
# speedup vs baseline: 1.0084x; 1.0084x over previous
.Lam96_nol2:
	global_load_dwordx4 v[98:101], v[244:245], off
	s_waitcnt lgkmcnt(11)
	v_mfma_f32_32x32x16_bf16 v[50:65], v[148:151], v[86:89], v[216:231]
	s_waitcnt lgkmcnt(10)
	v_mfma_f32_32x32x16_bf16 v[50:65], v[152:155], v[82:85], v[50:65]
	s_waitcnt lgkmcnt(9)
	v_mfma_f32_32x32x16_bf16 v[50:65], v[156:159], v[78:81], v[50:65]
	s_waitcnt lgkmcnt(8)
	v_mfma_f32_32x32x16_bf16 v[50:65], v[160:163], v[74:77], v[50:65]
	s_waitcnt lgkmcnt(7)
	v_mfma_f32_32x32x16_bf16 v[50:65], v[164:167], v[70:73], v[50:65]
	s_waitcnt lgkmcnt(6)
	v_mfma_f32_32x32x16_bf16 v[50:65], v[168:171], v[66:69], v[50:65]
	s_waitcnt lgkmcnt(5)
	v_mfma_f32_32x32x16_bf16 v[34:49], v[172:175], v[86:89], v[216:231]
	s_waitcnt lgkmcnt(4)
	v_mfma_f32_32x32x16_bf16 v[34:49], v[176:179], v[82:85], v[34:49]
	s_waitcnt lgkmcnt(3)
	v_mfma_f32_32x32x16_bf16 v[34:49], v[180:183], v[78:81], v[34:49]
	s_waitcnt lgkmcnt(2)
	v_mfma_f32_32x32x16_bf16 v[34:49], v[184:187], v[74:77], v[34:49]
	s_waitcnt lgkmcnt(1)
	v_mfma_f32_32x32x16_bf16 v[34:49], v[188:191], v[70:73], v[34:49]
	s_waitcnt lgkmcnt(0)
	v_mfma_f32_32x32x16_bf16 v[34:49], v[192:195], v[66:69], v[34:49]
	v_add3_u32 v144, s2, v127, v128
	v_add_u32_e32 v145, s2, v129
	ds_read_b64_tr_b16 v[148:149], v144 offset:12288
	ds_read_b64_tr_b16 v[150:151], v144 offset:13312
	ds_read_b64_tr_b16 v[152:153], v145 offset:12288
	ds_read_b64_tr_b16 v[154:155], v145 offset:13312
	ds_read_b64_tr_b16 v[156:157], v144 offset:14336
	ds_read_b64_tr_b16 v[158:159], v144 offset:15360
	ds_read_b64_tr_b16 v[160:161], v145 offset:14336
	ds_read_b64_tr_b16 v[162:163], v145 offset:15360
	ds_read_b64_tr_b16 v[164:165], v144 offset:16384
	ds_read_b64_tr_b16 v[166:167], v144 offset:17408
	ds_read_b64_tr_b16 v[168:169], v145 offset:16384
	ds_read_b64_tr_b16 v[170:171], v145 offset:17408
	v_max3_f32 v142, v50, v51, v52
	v_max3_f32 v142, v142, v53, v54
	v_max3_f32 v142, v142, v55, v56
	v_max3_f32 v142, v142, v57, v58
	v_max3_f32 v142, v142, v59, v60
	v_max3_f32 v142, v142, v61, v62
	v_max3_f32 v142, v142, v63, v64
	v_max3_f32 v143, v34, v35, v36
	v_max3_f32 v143, v143, v37, v38
	v_max3_f32 v143, v143, v39, v40
	v_max3_f32 v143, v143, v41, v42
	v_max3_f32 v143, v143, v43, v44
	v_max3_f32 v143, v143, v45, v46
	v_max3_f32 v143, v143, v47, v48
	v_max3_f32 v142, v142, v143, v65
	v_max_f32_e32 v142, v142, v49
	v_mov_b32_e32 v143, v142
	s_nop 1
	v_permlane32_swap_b32_e32 v142, v143
	v_max_f32_e32 v142, v142, v143
	s_mov_b32 s11, 0x41000000
	v_cmp_ge_f32_e64 s[42:43], s11, v142
	s_cmp_eq_u64 s[42:43], exec
	s_cbranch_scc0 .Lam96_resc
.Lam96_exp:
	v_exp_f32_e32 v50, v50
	v_exp_f32_e32 v51, v51
	v_exp_f32_e32 v52, v52
	v_exp_f32_e32 v53, v53
	v_exp_f32_e32 v54, v54
	v_exp_f32_e32 v55, v55
	v_exp_f32_e32 v56, v56
	v_exp_f32_e32 v57, v57
	v_cvt_pk_bf16_f32 v196, v50, v51
	v_cvt_pk_bf16_f32 v197, v52, v53
	v_cvt_pk_bf16_f32 v198, v54, v55
	v_cvt_pk_bf16_f32 v199, v56, v57
	v_add_f32_e32 v142, v50, v51
	v_add_f32_e32 v143, v52, v53
	v_add_f32_e32 v142, v142, v54
	v_add_f32_e32 v143, v143, v55
	v_add_f32_e32 v142, v142, v56
	v_add_f32_e32 v143, v143, v57
	v_add_f32_e32 v131, v131, v142
	v_add_f32_e32 v131, v131, v143
	s_waitcnt lgkmcnt(10)
	v_mfma_f32_32x32x16_bf16 v[18:33], v[148:151], v[196:199], v[18:33]
	s_waitcnt lgkmcnt(8)
	v_mfma_f32_32x32x16_bf16 v[2:17], v[152:155], v[196:199], v[2:17]
	ds_read_b64_tr_b16 v[172:173], v144 offset:18432
	ds_read_b64_tr_b16 v[174:175], v144 offset:19456
	ds_read_b64_tr_b16 v[176:177], v145 offset:18432
	ds_read_b64_tr_b16 v[178:179], v145 offset:19456
	v_exp_f32_e32 v58, v58
	v_exp_f32_e32 v59, v59
	v_exp_f32_e32 v60, v60
	v_exp_f32_e32 v61, v61
	v_exp_f32_e32 v62, v62
	v_exp_f32_e32 v63, v63
	v_exp_f32_e32 v64, v64
	v_exp_f32_e32 v65, v65
	v_cvt_pk_bf16_f32 v200, v58, v59
	v_cvt_pk_bf16_f32 v201, v60, v61
	v_cvt_pk_bf16_f32 v202, v62, v63
	v_cvt_pk_bf16_f32 v203, v64, v65
	v_add_f32_e32 v142, v58, v59
	v_add_f32_e32 v143, v60, v61
	v_add_f32_e32 v142, v142, v62
	v_add_f32_e32 v143, v143, v63
	v_add_f32_e32 v142, v142, v64
	v_add_f32_e32 v143, v143, v65
	v_add_f32_e32 v131, v131, v142
	v_add_f32_e32 v131, v131, v143
	s_waitcnt lgkmcnt(10)
	v_mfma_f32_32x32x16_bf16 v[18:33], v[156:159], v[200:203], v[18:33]
	s_waitcnt lgkmcnt(8)
	v_mfma_f32_32x32x16_bf16 v[2:17], v[160:163], v[200:203], v[2:17]
	v_exp_f32_e32 v34, v34
	v_exp_f32_e32 v35, v35
	v_exp_f32_e32 v36, v36
	v_exp_f32_e32 v37, v37
	v_exp_f32_e32 v38, v38
	v_exp_f32_e32 v39, v39
	v_exp_f32_e32 v40, v40
	v_exp_f32_e32 v41, v41
	v_cvt_pk_bf16_f32 v204, v34, v35
	v_cvt_pk_bf16_f32 v205, v36, v37
	v_cvt_pk_bf16_f32 v206, v38, v39
	v_cvt_pk_bf16_f32 v207, v40, v41
	v_add_f32_e32 v142, v34, v35
	v_add_f32_e32 v143, v36, v37
	v_add_f32_e32 v142, v142, v38
	v_add_f32_e32 v143, v143, v39
	v_add_f32_e32 v142, v142, v40
	v_add_f32_e32 v143, v143, v41
	v_add_f32_e32 v131, v131, v142
	v_add_f32_e32 v131, v131, v143
	s_waitcnt lgkmcnt(6)
	v_mfma_f32_32x32x16_bf16 v[18:33], v[164:167], v[204:207], v[18:33]
	s_waitcnt lgkmcnt(4)
	v_mfma_f32_32x32x16_bf16 v[2:17], v[168:171], v[204:207], v[2:17]
	v_exp_f32_e32 v42, v42
	v_exp_f32_e32 v43, v43
	v_exp_f32_e32 v44, v44
	v_exp_f32_e32 v45, v45
	v_exp_f32_e32 v46, v46
	v_exp_f32_e32 v47, v47
	v_exp_f32_e32 v48, v48
	v_exp_f32_e32 v49, v49
	v_cvt_pk_bf16_f32 v232, v42, v43
	v_cvt_pk_bf16_f32 v233, v44, v45
	v_cvt_pk_bf16_f32 v234, v46, v47
	v_cvt_pk_bf16_f32 v235, v48, v49
	v_add_f32_e32 v142, v42, v43
	v_add_f32_e32 v143, v44, v45
	v_add_f32_e32 v142, v142, v46
	v_add_f32_e32 v143, v143, v47
	v_add_f32_e32 v142, v142, v48
	v_add_f32_e32 v143, v143, v49
	v_add_f32_e32 v131, v131, v142
	v_add_f32_e32 v131, v131, v143
	s_waitcnt lgkmcnt(2)
	v_mfma_f32_32x32x16_bf16 v[18:33], v[172:175], v[232:235], v[18:33]
	s_waitcnt lgkmcnt(0)
	v_mfma_f32_32x32x16_bf16 v[2:17], v[176:179], v[232:235], v[2:17]
	s_bitcmp1_b32 s25, 0
	s_cselect_b32 s26, 0x5000, 0
	v_add3_u32 v138, s26, v119, v118
	v_add3_u32 v139, s26, v121, v120
	v_add3_u32 v140, s26, v122, v123
	s_waitcnt vmcnt(1)
	ds_write_b128 v138, v[94:97]
	s_and_b64 s[48:49], exec, s[38:39]
	s_cbranch_scc0 .Lam96_nos2
	ds_write_b128 v139, v[90:93]
	v_lshl_add_u64 v[242:243], v[242:243], 0, v[208:209]
.Lam96_nos2:
	s_waitcnt vmcnt(0)
	ds_write_b128 v140, v[98:101] offset:12288
	s_add_i32 s25, s25, 1
	s_mov_b32 s2, s26
	v_add_u32_e32 v138, s26, v125
	v_add_u32_e32 v139, s26, v126
	v_lshl_add_u64 v[240:241], v[240:241], 0, v[246:247]
	v_lshl_add_u64 v[244:245], v[244:245], 0, v[136:137]
	s_cmp_lg_u32 s25, 40
	s_waitcnt lgkmcnt(0)
	s_barrier
	s_cbranch_scc1 .Lam96_top
	s_mov_b32 s2, 0x41000000
	s_setprio 0
	s_branch .LBB0_333

.Lad64_ptr_ok:
	global_load_dwordx4 v[82:85], v[240:241], off
	global_load_dwordx4 v[86:89], v[242:243], off
	s_waitcnt lgkmcnt(7)
	v_mfma_f32_32x32x16_bf16 v[34:49], v[148:151], v[78:81], v[118:133]
	s_waitcnt lgkmcnt(6)
	v_mfma_f32_32x32x16_bf16 v[34:49], v[152:155], v[74:77], v[34:49]
	s_waitcnt lgkmcnt(5)
	v_mfma_f32_32x32x16_bf16 v[34:49], v[156:159], v[70:73], v[34:49]
	s_waitcnt lgkmcnt(4)
	v_mfma_f32_32x32x16_bf16 v[34:49], v[160:163], v[66:69], v[34:49]
	s_waitcnt lgkmcnt(3)
	v_mfma_f32_32x32x16_bf16 v[50:65], v[164:167], v[78:81], v[118:133]
	s_waitcnt lgkmcnt(2)
	v_mfma_f32_32x32x16_bf16 v[50:65], v[168:171], v[74:77], v[50:65]
	s_waitcnt lgkmcnt(1)
	v_mfma_f32_32x32x16_bf16 v[50:65], v[172:175], v[70:73], v[50:65]
	s_waitcnt lgkmcnt(0)
	v_mfma_f32_32x32x16_bf16 v[50:65], v[176:179], v[66:69], v[50:65]
	v_add3_u32 v134, s25, v115, v113
	v_add_u32_e32 v117, s25, v116
	ds_read_b64_tr_b16 v[180:181], v134 offset:8192
	ds_read_b64_tr_b16 v[182:183], v134 offset:9216
	ds_read_b64_tr_b16 v[184:185], v117 offset:8192
	ds_read_b64_tr_b16 v[186:187], v117 offset:9216
	ds_read_b64_tr_b16 v[188:189], v134 offset:10240
	ds_read_b64_tr_b16 v[190:191], v134 offset:11264
	ds_read_b64_tr_b16 v[192:193], v117 offset:10240
	ds_read_b64_tr_b16 v[194:195], v117 offset:11264
	ds_read_b64_tr_b16 v[196:197], v134 offset:12288
	ds_read_b64_tr_b16 v[198:199], v134 offset:13312
	ds_read_b64_tr_b16 v[200:201], v117 offset:12288
	ds_read_b64_tr_b16 v[202:203], v117 offset:13312
	v_max3_f32 v208, v34, v35, v36
	v_max3_f32 v208, v208, v37, v38
	v_max3_f32 v208, v208, v39, v40
	v_max3_f32 v208, v208, v41, v42
	v_max3_f32 v208, v208, v43, v44
	v_max3_f32 v208, v208, v45, v46
	v_max3_f32 v208, v208, v47, v48
	v_max3_f32 v209, v50, v51, v52
	v_max3_f32 v209, v209, v53, v54
	v_max3_f32 v209, v209, v55, v56
	v_max3_f32 v209, v209, v57, v58
	v_max3_f32 v209, v209, v59, v60
	v_max3_f32 v209, v209, v61, v62
	v_max3_f32 v209, v209, v63, v64
	v_max3_f32 v208, v208, v209, v49
	v_max_f32_e32 v208, v208, v65
	v_mov_b32_e32 v209, v208
	s_nop 1
	v_permlane32_swap_b32_e32 v208, v209
	v_max_f32_e32 v208, v208, v209
	v_cmp_ge_f32_e32 vcc, 0x41000000, v208
	s_cmp_eq_u64 vcc, exec
	s_cbranch_scc0 .Lad64_resc
.Lad64_exp:
	v_exp_f32_e32 v34, v34
	v_exp_f32_e32 v35, v35
	v_exp_f32_e32 v36, v36
	v_exp_f32_e32 v37, v37
	v_exp_f32_e32 v38, v38
	v_exp_f32_e32 v39, v39
	v_exp_f32_e32 v40, v40
	v_exp_f32_e32 v41, v41
	v_cvt_pk_bf16_f32 v220, v34, v35
	v_cvt_pk_bf16_f32 v221, v36, v37
	v_cvt_pk_bf16_f32 v222, v38, v39
	v_cvt_pk_bf16_f32 v223, v40, v41
	v_add_f32_e32 v208, v34, v35
	v_add_f32_e32 v209, v36, v37
	v_add_f32_e32 v208, v208, v38
	v_add_f32_e32 v209, v209, v39
	v_add_f32_e32 v208, v208, v40
	v_add_f32_e32 v209, v209, v41
	v_add_f32_e32 v96, v96, v208
	v_add_f32_e32 v96, v96, v209
	s_waitcnt lgkmcnt(10)
	v_mfma_f32_32x32x16_bf16 v[18:33], v[180:183], v[220:223], v[18:33]
	s_waitcnt lgkmcnt(8)
	v_mfma_f32_32x32x16_bf16 v[2:17], v[184:187], v[220:223], v[2:17]
	ds_read_b64_tr_b16 v[204:205], v134 offset:14336
	ds_read_b64_tr_b16 v[206:207], v134 offset:15360
	ds_read_b64_tr_b16 v[216:217], v117 offset:14336
	ds_read_b64_tr_b16 v[218:219], v117 offset:15360
	v_exp_f32_e32 v42, v42
	v_exp_f32_e32 v43, v43
	v_exp_f32_e32 v44, v44
	v_exp_f32_e32 v45, v45
	v_exp_f32_e32 v46, v46
	v_exp_f32_e32 v47, v47
	v_exp_f32_e32 v48, v48
	v_exp_f32_e32 v49, v49
	v_cvt_pk_bf16_f32 v224, v42, v43
	v_cvt_pk_bf16_f32 v225, v44, v45
	v_cvt_pk_bf16_f32 v226, v46, v47
	v_cvt_pk_bf16_f32 v227, v48, v49
	v_add_f32_e32 v208, v42, v43
	v_add_f32_e32 v209, v44, v45
	v_add_f32_e32 v208, v208, v46
	v_add_f32_e32 v209, v209, v47
	v_add_f32_e32 v208, v208, v48
	v_add_f32_e32 v209, v209, v49
	v_add_f32_e32 v96, v96, v208
	v_add_f32_e32 v96, v96, v209
	s_waitcnt lgkmcnt(10)
	v_mfma_f32_32x32x16_bf16 v[18:33], v[188:191], v[224:227], v[18:33]
	s_waitcnt lgkmcnt(8)
	v_mfma_f32_32x32x16_bf16 v[2:17], v[192:195], v[224:227], v[2:17]
	v_exp_f32_e32 v50, v50
	v_exp_f32_e32 v51, v51
	v_exp_f32_e32 v52, v52
	v_exp_f32_e32 v53, v53
	v_exp_f32_e32 v54, v54
	v_exp_f32_e32 v55, v55
	v_exp_f32_e32 v56, v56
	v_exp_f32_e32 v57, v57
	v_cvt_pk_bf16_f32 v228, v50, v51
	v_cvt_pk_bf16_f32 v229, v52, v53
	v_cvt_pk_bf16_f32 v230, v54, v55
	v_cvt_pk_bf16_f32 v231, v56, v57
	v_add_f32_e32 v208, v50, v51
	v_add_f32_e32 v209, v52, v53
	v_add_f32_e32 v208, v208, v54
	v_add_f32_e32 v209, v209, v55
	v_add_f32_e32 v208, v208, v56
	v_add_f32_e32 v209, v209, v57
	v_add_f32_e32 v96, v96, v208
	v_add_f32_e32 v96, v96, v209
	s_waitcnt lgkmcnt(6)
	v_mfma_f32_32x32x16_bf16 v[18:33], v[196:199], v[228:231], v[18:33]
	s_waitcnt lgkmcnt(4)
	v_mfma_f32_32x32x16_bf16 v[2:17], v[200:203], v[228:231], v[2:17]
	v_exp_f32_e32 v58, v58
	v_exp_f32_e32 v59, v59
	v_exp_f32_e32 v60, v60
	v_exp_f32_e32 v61, v61
	v_exp_f32_e32 v62, v62
	v_exp_f32_e32 v63, v63
	v_exp_f32_e32 v64, v64
	v_exp_f32_e32 v65, v65
	v_cvt_pk_bf16_f32 v232, v58, v59
	v_cvt_pk_bf16_f32 v233, v60, v61
	v_cvt_pk_bf16_f32 v234, v62, v63
	v_cvt_pk_bf16_f32 v235, v64, v65
	v_add_f32_e32 v208, v58, v59
	v_add_f32_e32 v209, v60, v61
	v_add_f32_e32 v208, v208, v62
	v_add_f32_e32 v209, v209, v63
	v_add_f32_e32 v208, v208, v64
	v_add_f32_e32 v209, v209, v65
	v_add_f32_e32 v96, v96, v208
	v_add_f32_e32 v96, v96, v209
	s_waitcnt lgkmcnt(2)
	v_mfma_f32_32x32x16_bf16 v[18:33], v[204:207], v[232:235], v[18:33]
	s_waitcnt lgkmcnt(0)
	v_mfma_f32_32x32x16_bf16 v[2:17], v[216:219], v[232:235], v[2:17]
	s_and_b32 s26, s24, 0x4000
	v_add3_u32 v134, s26, v106, v101
	v_add3_u32 v117, s26, v97, v99
	s_waitcnt vmcnt(1)
	ds_write_b128 v134, v[82:85]
	s_waitcnt vmcnt(0)
	ds_write_b128 v117, v[86:89] offset:8192
	s_add_i32 s10, s10, 1
	s_addk_i32 s24, 0x4000
	s_mov_b32 s25, s26
	v_add_u32_e32 v134, s26, v98
	v_add_u32_e32 v117, s26, v109
	v_add_u32_e32 v208, s26, v111
	v_add_u32_e32 v209, s26, v114
	v_lshl_add_u64 v[240:241], v[240:241], 0, v[244:245]
	v_lshl_add_u64 v[242:243], v[242:243], 0, v[244:245]
	s_cmp_lg_u32 s10, 39
	s_waitcnt lgkmcnt(0)
	s_barrier
	s_cbranch_scc1 .Lad64_top
	s_setprio 0
	s_branch .LBB0_345
